# static s_setprio 1 for waves 4-7 during the attention phase (reset to 0 at phase exit)
# baseline (speedup 1.0000x reference)
.LBB0_125:
	s_add_u32 s12, s0, s2
	s_addc_u32 s13, s1, s3
	global_load_dwordx4 v[2:5], v185, s[12:13] offset:16
	global_load_dwordx4 v[6:9], v185, s[12:13]
	s_add_u32 s12, s6, s2
	s_addc_u32 s13, s7, s3
	global_load_dwordx4 v[10:13], v185, s[12:13] offset:16
	global_load_dwordx4 v[14:17], v185, s[12:13]
	s_add_u32 s12, s10, s2
	s_addc_u32 s13, s11, s3
	global_load_dwordx4 v[18:21], v185, s[12:13] offset:16
	global_load_dwordx4 v[22:25], v185, s[12:13]
	s_add_u32 s12, s4, s2
	s_addc_u32 s13, s5, s3
	global_load_dwordx4 v[26:29], v185, s[12:13] offset:16
	global_load_dwordx4 v[30:33], v185, s[12:13]
	s_add_u32 s2, s2, 32
	s_addc_u32 s3, s3, 0
	s_cmpk_eq_i32 s2, 0x100
	s_waitcnt vmcnt(0)
	v_mov_b32_e32 v34, v6
	v_mov_b32_e32 v6, v8
	s_waitcnt vmcnt(5)
	v_mov_b32_e32 v8, v10
	s_waitcnt vmcnt(4)
	v_mov_b32_e32 v36, v14
	v_mov_b32_e32 v14, v16
	s_waitcnt vmcnt(2)
	v_mov_b32_e32 v35, v22
	v_mov_b32_e32 v22, v7
	v_mov_b32_e32 v7, v24
	s_waitcnt vmcnt(0)
	v_mov_b32_e32 v37, v30
	v_pk_fma_f32 v[0:1], v[34:35], v[36:37], v[0:1]
	v_mov_b32_e32 v30, v15
	v_pk_fma_f32 v[0:1], v[22:23], v[30:31], v[0:1]
	v_mov_b32_e32 v15, v32
	v_pk_fma_f32 v[0:1], v[6:7], v[14:15], v[0:1]
	v_mov_b32_e32 v24, v9
	v_mov_b32_e32 v32, v17
	v_pk_fma_f32 v[0:1], v[24:25], v[32:33], v[0:1]
	v_mov_b32_e32 v6, v2
	v_mov_b32_e32 v7, v18
	v_mov_b32_e32 v9, v26
	v_pk_fma_f32 v[0:1], v[6:7], v[8:9], v[0:1]
	v_mov_b32_e32 v18, v3
	v_mov_b32_e32 v26, v11
	v_pk_fma_f32 v[0:1], v[18:19], v[26:27], v[0:1]
	v_mov_b32_e32 v2, v4
	v_mov_b32_e32 v3, v20
	v_mov_b32_e32 v6, v12
	v_mov_b32_e32 v7, v28
	v_pk_fma_f32 v[0:1], v[2:3], v[6:7], v[0:1]
	v_mov_b32_e32 v20, v5
	v_mov_b32_e32 v28, v13
	v_pk_fma_f32 v[0:1], v[20:21], v[28:29], v[0:1]
	s_cbranch_scc0 .LBB0_125
	v_readlane_b32 s0, v253, 18
	v_readlane_b32 s1, v253, 19
	s_andn2_b64 vcc, exec, s[0:1]
	s_cbranch_vccnz .LBB0_187
	v_readlane_b32 s0, v254, 54
	v_readlane_b32 s1, v254, 55
	v_mov_b32_e32 v2, 0x3eb60549
	v_mov_b32_e32 v3, 0x3e4ccccd
	v_cndmask_b32_e64 v2, v2, v3, s[0:1]
	s_lshl_b32 s0, s35, 7
	v_mul_f32_e32 v0, 0x3fb8aa3b, v0
	v_mul_f32_e32 v1, 0x3fb8aa3b, v1
	s_ashr_i32 s1, s0, 31
	v_exp_f32_e32 v0, v0
	v_exp_f32_e32 v1, v1
	s_lshl_b64 s[0:1], s[0:1], 2
	v_readlane_b32 s60, v254, 18
	v_readlane_b32 s61, v254, 19
	s_add_u32 s10, s60, s0
	s_addc_u32 s11, s61, s1
	v_readlane_b32 s0, v253, 20
	v_readlane_b32 s1, v253, 21
	s_add_u32 s0, s94, s0
	v_sub_f32_e32 v0, v0, v1
	s_addc_u32 s1, s95, s1
	v_add_f32_e32 v144, v2, v0
	v_readlane_b32 s62, v254, 20
	v_readlane_b32 s63, v254, 21
	s_add_u32 s12, s0, 0x3800000
	s_mov_b32 s62, 0x41380000
	s_movk_i32 s60, 0xc0
	s_addc_u32 s13, s1, 0
	v_sub_f32_e32 v157, 1.0, v2
	v_mov_b32_e32 v145, v144
	v_readlane_b32 s63, v253, 10
	v_readlane_b32 s64, v254, 22
	v_readlane_b32 s65, v254, 23
	v_readlane_b32 s66, v254, 24
	v_readlane_b32 s67, v254, 25
	v_readlane_b32 s68, v254, 26
	v_readlane_b32 s69, v254, 27
	v_readlane_b32 s70, v254, 28
	v_readlane_b32 s71, v254, 29
	v_readlane_b32 s72, v254, 30
	v_readlane_b32 s73, v254, 31
	v_readlane_b32 s74, v254, 32
	v_readlane_b32 s75, v254, 33
	v_readfirstlane_b32 s0, v218
	s_nop 3
	s_lshr_b32 s0, s0, 6
	s_cmp_lt_u32 s0, 4
	s_cbranch_scc1 .Lprio_skip
	s_setprio 1
.Lprio_skip:
	s_branch .LBB0_130
.LBB0_128:
	s_or_b64 exec, exec, s[0:1]
	s_waitcnt lgkmcnt(0)
	v_add_u32_e32 v72, v159, v184
	ds_read_b128 v[64:67], v72
	ds_read_b128 v[68:71], v72 offset:32
	v_and_b32_e32 v73, 31, v158
	v_lshlrev_b32_e32 v184, 1, v73
	s_mov_b64 s[0:1], 0x400
	s_waitcnt lgkmcnt(1)
	v_rcp_f32_e32 v74, v64
	v_rcp_f32_e32 v75, v65
	v_rcp_f32_e32 v76, v66
	v_rcp_f32_e32 v77, v67
	ds_read_b128 v[64:67], v72 offset:64
	s_waitcnt lgkmcnt(1)
	v_rcp_f32_e32 v78, v68
	v_rcp_f32_e32 v79, v69
	v_rcp_f32_e32 v80, v70
	v_rcp_f32_e32 v81, v71
	ds_read_b128 v[68:71], v72 offset:96
	s_waitcnt lgkmcnt(1)
	v_rcp_f32_e32 v72, v64
	v_rcp_f32_e32 v82, v65
	v_lshrrev_b32_e32 v64, 1, v158
	v_lshrrev_b32_e32 v65, 3, v158
	v_and_b32_e32 v64, 32, v64
	v_and_b32_e32 v65, 4, v65
	v_or3_b32 v64, v64, v65, s14
	v_mov_b32_e32 v65, s15
	v_rcp_f32_e32 v83, v66
	v_lshlrev_b64 v[64:65], 11, v[64:65]
	v_and_b32_e32 v66, 0xffffff80, v158
	v_rcp_f32_e32 v84, v67
	v_lshl_add_u64 v[64:65], s[8:9], 0, v[64:65]
	v_ashrrev_i32_e32 v67, 31, v66
	v_lshl_add_u64 v[64:65], v[66:67], 1, v[64:65]
	v_lshl_add_u64 v[64:65], v[64:65], 0, v[184:185]
	v_lshl_add_u64 v[66:67], v[64:65], 0, s[0:1]
	v_mul_f32_e32 v48, v48, v74
	v_mul_f32_e32 v32, v32, v74
	v_mul_f32_e32 v16, v16, v74
	v_mul_f32_e32 v0, v0, v74
	v_cvt_pk_bf16_f32 v48, v48, v48
	flat_store_short v[66:67], v48
	v_cvt_pk_bf16_f32 v32, v32, v32
	flat_store_short v[66:67], v32 offset:64
	v_cvt_pk_bf16_f32 v16, v16, v16
	flat_store_short v[66:67], v16 offset:128
	v_cvt_pk_bf16_f32 v0, v0, v0
	s_mov_b64 s[0:1], 0xc00
	flat_store_short v[66:67], v0 offset:192
	v_lshl_add_u64 v[66:67], v[64:65], 0, s[0:1]
	v_mul_f32_e32 v0, v49, v75
	v_cvt_pk_bf16_f32 v0, v0, v0
	flat_store_short v[66:67], v0
	v_mul_f32_e32 v0, v33, v75
	v_cvt_pk_bf16_f32 v0, v0, v0
	flat_store_short v[66:67], v0 offset:64
	v_mul_f32_e32 v0, v17, v75
	v_cvt_pk_bf16_f32 v0, v0, v0
	flat_store_short v[66:67], v0 offset:128
	v_mul_f32_e32 v0, v1, v75
	v_cvt_pk_bf16_f32 v0, v0, v0
	s_mov_b64 s[0:1], 0x1400
	flat_store_short v[66:67], v0 offset:192
	v_lshl_add_u64 v[0:1], v[64:65], 0, s[0:1]
	v_mul_f32_e32 v16, v50, v76
	v_cvt_pk_bf16_f32 v16, v16, v16
	flat_store_short v[0:1], v16
	v_mul_f32_e32 v16, v34, v76
	v_cvt_pk_bf16_f32 v16, v16, v16
	flat_store_short v[0:1], v16 offset:64
	v_mul_f32_e32 v16, v18, v76
	v_mul_f32_e32 v2, v2, v76
	v_cvt_pk_bf16_f32 v16, v16, v16
	flat_store_short v[0:1], v16 offset:128
	v_cvt_pk_bf16_f32 v2, v2, v2
	s_mov_b64 s[0:1], 0x1c00
	flat_store_short v[0:1], v2 offset:192
	v_lshl_add_u64 v[0:1], v[64:65], 0, s[0:1]
	v_mul_f32_e32 v2, v51, v77
	v_cvt_pk_bf16_f32 v2, v2, v2
	flat_store_short v[0:1], v2
	v_mul_f32_e32 v2, v35, v77
	v_cvt_pk_bf16_f32 v2, v2, v2
	flat_store_short v[0:1], v2 offset:64
	v_mul_f32_e32 v2, v19, v77
	v_cvt_pk_bf16_f32 v2, v2, v2
	flat_store_short v[0:1], v2 offset:128
	v_mul_f32_e32 v2, v3, v77
	v_cvt_pk_bf16_f32 v2, v2, v2
	s_mov_b64 s[0:1], 0x4400
	flat_store_short v[0:1], v2 offset:192
	v_lshl_add_u64 v[0:1], v[64:65], 0, s[0:1]
	v_mul_f32_e32 v2, v52, v78
	v_cvt_pk_bf16_f32 v2, v2, v2
	flat_store_short v[0:1], v2
	v_mul_f32_e32 v2, v36, v78
	v_cvt_pk_bf16_f32 v2, v2, v2
	flat_store_short v[0:1], v2 offset:64
	v_mul_f32_e32 v2, v20, v78
	v_cvt_pk_bf16_f32 v2, v2, v2
	flat_store_short v[0:1], v2 offset:128
	v_mul_f32_e32 v2, v4, v78
	v_cvt_pk_bf16_f32 v2, v2, v2
	s_mov_b64 s[0:1], 0x4c00
	flat_store_short v[0:1], v2 offset:192
	v_lshl_add_u64 v[0:1], v[64:65], 0, s[0:1]
	v_mul_f32_e32 v2, v53, v79
	v_cvt_pk_bf16_f32 v2, v2, v2
	flat_store_short v[0:1], v2
	v_mul_f32_e32 v2, v37, v79
	v_cvt_pk_bf16_f32 v2, v2, v2
	flat_store_short v[0:1], v2 offset:64
	v_mul_f32_e32 v2, v21, v79
	v_cvt_pk_bf16_f32 v2, v2, v2
	flat_store_short v[0:1], v2 offset:128
	v_mul_f32_e32 v2, v5, v79
	v_cvt_pk_bf16_f32 v2, v2, v2
	flat_store_short v[0:1], v2 offset:192
	v_lshl_add_u64 v[0:1], v[64:65], 0, s[92:93]
	v_mul_f32_e32 v2, v54, v80
	v_cvt_pk_bf16_f32 v2, v2, v2
	flat_store_short v[0:1], v2
	v_mul_f32_e32 v2, v38, v80
	v_cvt_pk_bf16_f32 v2, v2, v2
	flat_store_short v[0:1], v2 offset:64
	v_mul_f32_e32 v2, v22, v80
	v_cvt_pk_bf16_f32 v2, v2, v2
	flat_store_short v[0:1], v2 offset:128
	v_mul_f32_e32 v2, v6, v80
	v_cvt_pk_bf16_f32 v2, v2, v2
	s_mov_b64 s[0:1], 0x5c00
	flat_store_short v[0:1], v2 offset:192
	v_lshl_add_u64 v[0:1], v[64:65], 0, s[0:1]
	v_mul_f32_e32 v2, v55, v81
	v_cvt_pk_bf16_f32 v2, v2, v2
	flat_store_short v[0:1], v2
	v_mul_f32_e32 v2, v39, v81
	v_cvt_pk_bf16_f32 v2, v2, v2
	flat_store_short v[0:1], v2 offset:64
	v_mul_f32_e32 v2, v23, v81
	v_cvt_pk_bf16_f32 v2, v2, v2
	flat_store_short v[0:1], v2 offset:128
	v_mul_f32_e32 v2, v7, v81
	v_cvt_pk_bf16_f32 v2, v2, v2
	s_mov_b64 s[0:1], 0x8400
	flat_store_short v[0:1], v2 offset:192
	v_lshl_add_u64 v[0:1], v[64:65], 0, s[0:1]
	v_mul_f32_e32 v2, v56, v72
	v_cvt_pk_bf16_f32 v2, v2, v2
	flat_store_short v[0:1], v2
	v_mul_f32_e32 v2, v40, v72
	v_cvt_pk_bf16_f32 v2, v2, v2
	flat_store_short v[0:1], v2 offset:64
	v_mul_f32_e32 v2, v24, v72
	v_cvt_pk_bf16_f32 v2, v2, v2
	flat_store_short v[0:1], v2 offset:128
	v_mul_f32_e32 v2, v8, v72
	v_cvt_pk_bf16_f32 v2, v2, v2
	s_mov_b64 s[0:1], 0x8c00
	flat_store_short v[0:1], v2 offset:192
	v_lshl_add_u64 v[0:1], v[64:65], 0, s[0:1]
	v_mul_f32_e32 v2, v57, v82
	v_cvt_pk_bf16_f32 v2, v2, v2
	flat_store_short v[0:1], v2
	v_mul_f32_e32 v2, v41, v82
	v_cvt_pk_bf16_f32 v2, v2, v2
	flat_store_short v[0:1], v2 offset:64
	v_mul_f32_e32 v2, v25, v82
	v_cvt_pk_bf16_f32 v2, v2, v2
	flat_store_short v[0:1], v2 offset:128
	v_mul_f32_e32 v2, v9, v82
	v_cvt_pk_bf16_f32 v2, v2, v2
	s_mov_b64 s[0:1], 0x9400
	flat_store_short v[0:1], v2 offset:192
	v_lshl_add_u64 v[0:1], v[64:65], 0, s[0:1]
	v_mul_f32_e32 v2, v58, v83
	v_cvt_pk_bf16_f32 v2, v2, v2
	flat_store_short v[0:1], v2
	v_mul_f32_e32 v2, v42, v83
	v_cvt_pk_bf16_f32 v2, v2, v2
	flat_store_short v[0:1], v2 offset:64
	v_mul_f32_e32 v2, v26, v83
	v_cvt_pk_bf16_f32 v2, v2, v2
	flat_store_short v[0:1], v2 offset:128
	v_mul_f32_e32 v2, v10, v83
	v_cvt_pk_bf16_f32 v2, v2, v2
	s_mov_b64 s[0:1], 0x9c00
	flat_store_short v[0:1], v2 offset:192
	v_lshl_add_u64 v[0:1], v[64:65], 0, s[0:1]
	v_mul_f32_e32 v2, v59, v84
	v_cvt_pk_bf16_f32 v2, v2, v2
	flat_store_short v[0:1], v2
	v_mul_f32_e32 v2, v43, v84
	v_cvt_pk_bf16_f32 v2, v2, v2
	s_waitcnt lgkmcnt(0)
	v_rcp_f32_e32 v68, v68
	flat_store_short v[0:1], v2 offset:64
	v_mul_f32_e32 v2, v27, v84
	v_cvt_pk_bf16_f32 v2, v2, v2
	flat_store_short v[0:1], v2 offset:128
	v_mul_f32_e32 v2, v11, v84
	v_cvt_pk_bf16_f32 v2, v2, v2
	s_mov_b64 s[0:1], 0xc400
	flat_store_short v[0:1], v2 offset:192
	v_lshl_add_u64 v[0:1], v[64:65], 0, s[0:1]
	v_mul_f32_e32 v2, v60, v68
	v_cvt_pk_bf16_f32 v2, v2, v2
	flat_store_short v[0:1], v2
	v_mul_f32_e32 v2, v44, v68
	v_cvt_pk_bf16_f32 v2, v2, v2
	v_rcp_f32_e32 v69, v69
	flat_store_short v[0:1], v2 offset:64
	v_mul_f32_e32 v2, v28, v68
	v_cvt_pk_bf16_f32 v2, v2, v2
	flat_store_short v[0:1], v2 offset:128
	v_mul_f32_e32 v2, v12, v68
	v_cvt_pk_bf16_f32 v2, v2, v2
	s_mov_b64 s[0:1], 0xcc00
	flat_store_short v[0:1], v2 offset:192
	v_lshl_add_u64 v[0:1], v[64:65], 0, s[0:1]
	v_mul_f32_e32 v2, v61, v69
	v_cvt_pk_bf16_f32 v2, v2, v2
	flat_store_short v[0:1], v2
	v_mul_f32_e32 v2, v45, v69
	v_cvt_pk_bf16_f32 v2, v2, v2
	v_rcp_f32_e32 v70, v70
	flat_store_short v[0:1], v2 offset:64
	v_mul_f32_e32 v2, v29, v69
	v_cvt_pk_bf16_f32 v2, v2, v2
	flat_store_short v[0:1], v2 offset:128
	v_mul_f32_e32 v2, v13, v69
	v_cvt_pk_bf16_f32 v2, v2, v2
	s_mov_b64 s[0:1], 0xd400
	flat_store_short v[0:1], v2 offset:192
	v_lshl_add_u64 v[0:1], v[64:65], 0, s[0:1]
	v_mul_f32_e32 v2, v62, v70
	v_cvt_pk_bf16_f32 v2, v2, v2
	flat_store_short v[0:1], v2
	v_mul_f32_e32 v2, v46, v70
	v_cvt_pk_bf16_f32 v2, v2, v2
	v_rcp_f32_e32 v71, v71
	flat_store_short v[0:1], v2 offset:64
	v_mul_f32_e32 v2, v30, v70
	v_cvt_pk_bf16_f32 v2, v2, v2
	flat_store_short v[0:1], v2 offset:128
	v_mul_f32_e32 v2, v14, v70
	v_cvt_pk_bf16_f32 v2, v2, v2
	s_mov_b64 s[0:1], 0xdc00
	flat_store_short v[0:1], v2 offset:192
	v_lshl_add_u64 v[0:1], v[64:65], 0, s[0:1]
	v_mul_f32_e32 v2, v63, v71
	v_cvt_pk_bf16_f32 v2, v2, v2
	flat_store_short v[0:1], v2
	v_mul_f32_e32 v2, v47, v71
	v_cvt_pk_bf16_f32 v2, v2, v2
	flat_store_short v[0:1], v2 offset:64
	v_mul_f32_e32 v2, v31, v71
	v_cvt_pk_bf16_f32 v2, v2, v2
	flat_store_short v[0:1], v2 offset:128
	v_mul_f32_e32 v2, v15, v71
	v_cvt_pk_bf16_f32 v2, v2, v2

.LBB0_187:
	s_setprio 0
	v_readlane_b32 s60, v254, 46
	s_waitcnt lgkmcnt(0)
	s_barrier
	s_mov_b64 s[0:1], 0
	v_readlane_b32 s61, v254, 47
